# before the class barriers, waves 1-7 touch the first two K-tiles of the next phase's weight tile (L2 prefetch across the barrier)
# baseline (speedup 1.0000x reference)
.LBB0_634:
	s_or_b64 exec, exec, s[14:15]
	s_mov_b32 s53, 0x7ffff
	s_waitcnt vmcnt(0)
	s_barrier
	v_readlane_b32 s0, v211, 0
	s_cmp_lt_u32 s0, 64
	s_cbranch_scc1 .Lbpf686_skip
	s_lshr_b32 s0, s74, 6
	s_lshl_b32 s0, s0, 8
	v_subrev_u32_e32 v252, 64, v211
	v_lshrrev_b32_e32 v253, 1, v252
	v_add_u32_e32 v253, s0, v253
	v_mul_u32_u24_e32 v253, 0x800, v253
	v_and_b32_e32 v247, 1, v252
	v_lshl_add_u32 v253, v247, 7, v253
	v_and_b32_e32 v247, 63, v252
	v_add_u32_e32 v247, 0x1c0, v247
	v_lshrrev_b32_e32 v246, 1, v247
	v_add_u32_e32 v246, s0, v246
	v_mul_u32_u24_e32 v246, 0x800, v246
	v_and_b32_e32 v247, 1, v247
	v_lshl_add_u32 v246, v247, 7, v246
	s_add_u32 s2, s92, 0x810000
	s_addc_u32 s3, s93, 0
	global_load_dword v253, v253, s[2:3]
	global_load_dword v246, v246, s[2:3]
.Lbpf686_skip:
	v_readlane_b32 s0, v211, 0
	s_cmp_eq_u32 s0, 64
	s_cbranch_scc0 .Llb686_w1
	buffer_inv sc1
	s_waitcnt vmcnt(0)

.LBB0_738:
	s_waitcnt vmcnt(0)
	s_barrier
	v_readlane_b32 s0, v211, 0
	s_cmp_lt_u32 s0, 64
	s_cbranch_scc1 .Lbpf790_skip
	s_lshr_b32 s0, s74, 6
	s_lshl_b32 s0, s0, 8
	v_subrev_u32_e32 v252, 64, v211
	v_lshrrev_b32_e32 v253, 1, v252
	v_add_u32_e32 v253, s0, v253
	v_mul_u32_u24_e32 v253, 0x800, v253
	v_and_b32_e32 v247, 1, v252
	v_lshl_add_u32 v253, v247, 7, v253
	v_and_b32_e32 v247, 63, v252
	v_add_u32_e32 v247, 0x1c0, v247
	v_lshrrev_b32_e32 v246, 1, v247
	v_add_u32_e32 v246, s0, v246
	v_mul_u32_u24_e32 v246, 0x800, v246
	v_and_b32_e32 v247, 1, v247
	v_lshl_add_u32 v246, v247, 7, v246
	s_add_u32 s2, s92, 0xa10000
	s_addc_u32 s3, s93, 0
	global_load_dword v253, v253, s[2:3]
	global_load_dword v246, v246, s[2:3]

.LBB0_830:
	s_waitcnt vmcnt(0)
	s_waitcnt vmcnt(0)
	s_barrier
	v_readlane_b32 s0, v211, 0
	s_cmp_lt_u32 s0, 64
	s_cbranch_scc1 .Lbpf882_skip
	s_lshr_b32 s0, s74, 6
	s_lshl_b32 s0, s0, 8
	v_subrev_u32_e32 v252, 64, v211
	v_lshrrev_b32_e32 v253, 1, v252
	v_add_u32_e32 v253, s0, v253
	v_mul_u32_u24_e32 v253, 0x1600, v253
	v_and_b32_e32 v247, 1, v252
	v_lshl_add_u32 v253, v247, 7, v253
	v_and_b32_e32 v247, 63, v252
	v_add_u32_e32 v247, 0x1c0, v247
	v_lshrrev_b32_e32 v246, 1, v247
	v_add_u32_e32 v246, s0, v246
	v_mul_u32_u24_e32 v246, 0x1600, v246
	v_and_b32_e32 v247, 1, v247
	v_lshl_add_u32 v246, v247, 7, v246
	s_add_u32 s2, s92, 0x1510000
	s_addc_u32 s3, s93, 0
	global_load_dword v253, v253, s[2:3]
	global_load_dword v246, v246, s[2:3]

.LBB0_910:
	s_waitcnt vmcnt(0)
	s_barrier
	v_readlane_b32 s0, v211, 0
	s_cmp_lt_u32 s0, 64
	s_cbranch_scc1 .Lbpf962_skip
	s_lshr_b32 s0, s74, 6
	s_lshl_b32 s0, s0, 8
	v_subrev_u32_e32 v252, 64, v211
	v_lshrrev_b32_e32 v253, 1, v252
	v_add_u32_e32 v253, s0, v253
	v_mul_u32_u24_e32 v253, 0x800, v253
	v_and_b32_e32 v247, 1, v252
	v_lshl_add_u32 v253, v247, 7, v253
	v_and_b32_e32 v247, 63, v252
	v_add_u32_e32 v247, 0x1c0, v247
	v_lshrrev_b32_e32 v246, 1, v247
	v_add_u32_e32 v246, s0, v246
	v_mul_u32_u24_e32 v246, 0x800, v246
	v_and_b32_e32 v247, 1, v247
	v_lshl_add_u32 v246, v247, 7, v246
	s_add_u32 s2, s92, 0x1a90000
	s_addc_u32 s3, s93, 0
	global_load_dword v253, v253, s[2:3]
	global_load_dword v246, v246, s[2:3]
